# v96 + attention lazy-rescale threshold 8 -> 12 log2 units (fewer rescale-block executions)
# speedup vs baseline: 1.0028x; 1.0028x over previous
; #define LAS __attribute__((address_space(3)))
; DI float shfl_xor_l(float v, int lane, int m) { return __int_as_float(__builtin_amdgcn_ds_bpermute((lane ^ m) << 2, __float_as_int(v))); }
; #define A_LOAD(kt) do { const size_t ko = (size_t)(kt) * 64; st0 = *(const u32x4*)(kn_src + ko * 2048); st1 = *(const u32x4*)(kn_src + (ko + 32) * 2048); \
;         st2 = *(const u32x4*)(kr_src + ko * 64); st3 = *(const u32x4*)(v_src + ko); st4 = *(const u32x4*)(v_src + ko + (size_t)64 * 8192); } while (0)
; #define VLD(dst, j, dt) do { LAS unsigned char* va_ = vb + (32 * (dt) + n) * VROW + (16 * (j) + 4 * g) * 2; const u32x2 lo_ = *(const LAS u32x2*)(va_), hi_ = *(const LAS u32x2*)(va_ + 16); dst = (u32x4){lo_.x, lo_.y, hi_.x, hi_.y}; } while (0)
; DI void attn_unit(LAS unsigned char* lds, int wid, int b, int h, int qb) {
;     ...
;     for (int kt = 0; kt < nkt; ++kt) {
;         const int buf = kt & 1;
;         if (kt + 1 < nkt) A_LOAD(kt + 1);
;         if (kt <= cq) {
;             LAS unsigned char* kb = lds + buf * ABUF; LAS unsigned char* vb = kb + KBYTES;
;             f32x16 s0, s1;
; #pragma unroll
;             for (int i = 0; i < 16; ++i) { s0[i] = 0.f; s1[i] = 0.f; }
;     ...
;             bf16x8 ka[3][2];
;             ka[0][0] = KLD(0, 0); ka[0][1] = KLD(0, 1); ka[1][0] = KLD(1, 0); ka[1][1] = KLD(1, 1);
; #pragma unroll
;             for (int ks = 0; ks < 12; ++ks) {
;                 if (ks + 2 < 12) { ka[(ks + 2) % 3][0] = KLD(ks + 2, 0); ka[(ks + 2) % 3][1] = KLD(ks + 2, 1); }
;                 s0 = __builtin_amdgcn_mfma_f32_32x32x16_bf16(ka[ks % 3][0], qf[ks], s0, 0, 0, 0); s1 = __builtin_amdgcn_mfma_f32_32x32x16_bf16(ka[ks % 3][1], qf[ks], s1, 0, 0, 0);
;                 __builtin_amdgcn_sched_barrier(0); }
;             u32x4 vf[2][4];
; #pragma unroll
;             for (int dt = 0; dt < 4; ++dt) VLD(vf[0][dt], 0, dt);
;             float mx = s0[0];
; #pragma unroll
;             for (int i = 1; i < 16; ++i) mx = fmaxf(mx, s0[i]);
; #pragma unroll
;             for (int i = 0; i < 16; ++i) mx = fmaxf(mx, s1[i]);
;             mx = fmaxf(mx, shfl_xor_l(mx, lane, 32));
;             const float mnew = fmaxf(mrow, mx), alpha = __builtin_amdgcn_exp2f(mrow - mnew); mrow = mnew;
.LBB0_1079:
	s_and_b32 s65, s64, 1
	global_load_dwordx4 v[146:149], v194, s[70:71]
	global_load_dwordx4 v[150:153], v194, s[72:73]
	global_load_dwordx4 v[154:157], v192, s[78:79]
	global_load_dwordx4 v[158:161], v190, s[74:75] offset:128
	global_load_dwordx4 v[162:165], v190, s[76:77] offset:128
	s_cmp_gt_u32 s64, s62
	s_cbranch_scc1 .LBB0_1083
	s_mul_i32 s66, s65, 0xa800
	s_add_i32 s66, s66, 0
	v_add3_u32 v171, s66, v199, v202
	ds_read_b128 v[66:69], v171
	ds_read_b128 v[166:169], v171 offset:32
	ds_read_b128 v[82:85], v171 offset:12800
	ds_read_b128 v[172:175], v171 offset:64
	ds_read_b128 v[176:179], v171 offset:12832
	ds_read_b128 v[204:207], v171 offset:12864
	s_waitcnt lgkmcnt(3)
	v_mfma_f32_32x32x16_bf16 v[82:97], v[82:85], v[142:145], v[216:231]
	v_mfma_f32_32x32x16_bf16 v[66:81], v[66:69], v[142:145], v[216:231]
	v_mfma_f32_32x32x16_bf16 v[66:81], v[166:169], v[138:141], v[66:81]
	ds_read_b128 v[166:169], v171 offset:96
	ds_read_b128 v[208:211], v171 offset:12896
	s_waitcnt lgkmcnt(3)
	v_mfma_f32_32x32x16_bf16 v[82:97], v[176:179], v[138:141], v[82:97]
	v_mfma_f32_32x32x16_bf16 v[66:81], v[172:175], v[134:137], v[66:81]
	ds_read_b128 v[172:175], v171 offset:128
	ds_read_b128 v[176:179], v171 offset:12928
	s_waitcnt lgkmcnt(4)
	v_mfma_f32_32x32x16_bf16 v[82:97], v[204:207], v[134:137], v[82:97]
	s_waitcnt lgkmcnt(3)
	v_mfma_f32_32x32x16_bf16 v[66:81], v[166:169], v[130:133], v[66:81]
	ds_read_b128 v[166:169], v171 offset:160
	ds_read_b128 v[204:207], v171 offset:12960
	s_waitcnt lgkmcnt(4)
	v_mfma_f32_32x32x16_bf16 v[82:97], v[208:211], v[130:133], v[82:97]
	s_waitcnt lgkmcnt(3)
	v_mfma_f32_32x32x16_bf16 v[66:81], v[172:175], v[126:129], v[66:81]
	ds_read_b128 v[172:175], v171 offset:192
	ds_read_b128 v[208:211], v171 offset:12992
	s_waitcnt lgkmcnt(4)
	v_mfma_f32_32x32x16_bf16 v[82:97], v[176:179], v[126:129], v[82:97]
	s_waitcnt lgkmcnt(3)
	v_mfma_f32_32x32x16_bf16 v[66:81], v[166:169], v[122:125], v[66:81]
	ds_read_b128 v[166:169], v171 offset:224
	ds_read_b128 v[176:179], v171 offset:13024
	s_waitcnt lgkmcnt(4)
	v_mfma_f32_32x32x16_bf16 v[82:97], v[204:207], v[122:125], v[82:97]
	s_waitcnt lgkmcnt(3)
	v_mfma_f32_32x32x16_bf16 v[66:81], v[172:175], v[118:121], v[66:81]
	ds_read_b128 v[172:175], v171 offset:256
	ds_read_b128 v[204:207], v171 offset:13056
	s_waitcnt lgkmcnt(4)
	v_mfma_f32_32x32x16_bf16 v[82:97], v[208:211], v[118:121], v[82:97]
	s_waitcnt lgkmcnt(3)
	v_mfma_f32_32x32x16_bf16 v[66:81], v[166:169], v[114:117], v[66:81]
	ds_read_b128 v[166:169], v171 offset:288
	ds_read_b128 v[208:211], v171 offset:13088
	s_waitcnt lgkmcnt(4)
	v_mfma_f32_32x32x16_bf16 v[82:97], v[176:179], v[114:117], v[82:97]
	s_waitcnt lgkmcnt(3)
	v_mfma_f32_32x32x16_bf16 v[66:81], v[172:175], v[110:113], v[66:81]
	ds_read_b128 v[172:175], v171 offset:320
	ds_read_b128 v[176:179], v171 offset:13120
	s_waitcnt lgkmcnt(4)
	v_mfma_f32_32x32x16_bf16 v[82:97], v[204:207], v[110:113], v[82:97]
	s_waitcnt lgkmcnt(3)
	v_mfma_f32_32x32x16_bf16 v[66:81], v[166:169], v[106:109], v[66:81]
	ds_read_b128 v[166:169], v171 offset:352
	ds_read_b128 v[212:215], v171 offset:13152
	s_waitcnt lgkmcnt(4)
	v_mfma_f32_32x32x16_bf16 v[82:97], v[208:211], v[106:109], v[82:97]
	s_waitcnt lgkmcnt(3)
	v_mfma_f32_32x32x16_bf16 v[66:81], v[172:175], v[102:105], v[66:81]
	s_waitcnt lgkmcnt(2)
	v_mfma_f32_32x32x16_bf16 v[82:97], v[176:179], v[102:105], v[82:97]
	s_waitcnt lgkmcnt(1)
	v_mfma_f32_32x32x16_bf16 v[66:81], v[166:169], v[98:101], v[66:81]
	v_add3_u32 v171, s66, v184, v189
	v_add_u32_e32 v204, 0x6000, v171
	v_add_u32_e32 v205, 0x7000, v171
	v_add_u32_e32 v206, 0x8000, v171
	v_add_u32_e32 v207, 0x9000, v171
	ds_read2_b64 v[166:169], v204 offset0:128 offset1:130
	s_nop 4
	v_max_f32_e32 v172, v66, v67
	s_waitcnt lgkmcnt(1)
	v_mfma_f32_32x32x16_bf16 v[82:97], v[212:215], v[98:101], v[82:97]
	v_max3_f32 v172, v172, v68, v69
	v_max3_f32 v172, v172, v70, v71
	v_max3_f32 v172, v172, v72, v73
	v_max3_f32 v172, v172, v74, v75
	v_max3_f32 v172, v172, v76, v77
	v_max3_f32 v172, v172, v78, v79
	v_max3_f32 v172, v172, v80, v81
	s_nop 4
	v_max3_f32 v172, v172, v82, v83
	v_max3_f32 v172, v172, v84, v85
	v_max3_f32 v172, v172, v86, v87
	v_max3_f32 v172, v172, v88, v89
	v_max3_f32 v172, v172, v90, v91
	v_max3_f32 v172, v172, v92, v93
	v_max3_f32 v172, v172, v94, v95
	v_max3_f32 v172, v172, v96, v97
	ds_read2_b64 v[178:181], v205 offset0:160 offset1:162
	ds_read2_b64 v[174:177], v206 offset0:192 offset1:194
	v_cmp_lt_f32_e32 vcc, 0x41400000, v172
	s_cmp_eq_u32 s64, 0
	s_cbranch_scc1 .Lfold_0_upd
	s_cbranch_vccnz .Lfold_0_upd

; #define LAS __attribute__((address_space(3)))
; DI float shfl_xor_l(float v, int lane, int m) { return __int_as_float(__builtin_amdgcn_ds_bpermute((lane ^ m) << 2, __float_as_int(v))); }
; #define VLD(dst, j, dt) do { LAS unsigned char* va_ = vb + (32 * (dt) + n) * VROW + (16 * (j) + 4 * g) * 2; const u32x2 lo_ = *(const LAS u32x2*)(va_), hi_ = *(const LAS u32x2*)(va_ + 16); dst = (u32x4){lo_.x, lo_.y, hi_.x, hi_.y}; } while (0)
; DI void attn_unit(LAS unsigned char* lds, int wid, int b, int h, int qb) {
;     ...
;         if (kt <= cq) {
;             LAS unsigned char* kb = lds + buf * ABUF; LAS unsigned char* vb = kb + KBYTES;
;             f32x16 s0, s1;
; #pragma unroll
;             for (int i = 0; i < 16; ++i) { s0[i] = 0.f; s1[i] = 0.f; }
;     ...
;             bf16x8 ka[3][2];
;             ka[0][0] = KLD(0, 0); ka[0][1] = KLD(0, 1); ka[1][0] = KLD(1, 0); ka[1][1] = KLD(1, 1);
; #pragma unroll
;             for (int ks = 0; ks < 12; ++ks) {
;                 if (ks + 2 < 12) { ka[(ks + 2) % 3][0] = KLD(ks + 2, 0); ka[(ks + 2) % 3][1] = KLD(ks + 2, 1); }
;                 s0 = __builtin_amdgcn_mfma_f32_32x32x16_bf16(ka[ks % 3][0], qf[ks], s0, 0, 0, 0); s1 = __builtin_amdgcn_mfma_f32_32x32x16_bf16(ka[ks % 3][1], qf[ks], s1, 0, 0, 0);
;                 __builtin_amdgcn_sched_barrier(0); }
;             u32x4 vf[2][4];
; #pragma unroll
;             for (int dt = 0; dt < 4; ++dt) VLD(vf[0][dt], 0, dt);
;             float mx = s0[0];
; #pragma unroll
;             for (int i = 1; i < 16; ++i) mx = fmaxf(mx, s0[i]);
; #pragma unroll
;             for (int i = 0; i < 16; ++i) mx = fmaxf(mx, s1[i]);
;             mx = fmaxf(mx, shfl_xor_l(mx, lane, 32));
;             const float mnew = fmaxf(mrow, mx), alpha = __builtin_amdgcn_exp2f(mrow - mnew); mrow = mnew;
;             float ls = 0.f;
; #pragma unroll
;             for (int i = 0; i < 16; ++i) { s0[i] = __builtin_amdgcn_exp2f(s0[i] - mnew); s1[i] = __builtin_amdgcn_exp2f(s1[i] - mnew); ls += s0[i] + s1[i]; }
;             lrow = lrow * alpha + ls;
;             if (__builtin_amdgcn_ballot_w64(alpha != 1.f) != 0ull) {
.LBB0_1086:
	s_or_b32 s61, s61, 2
	s_cmp_ge_u32 s61, s62
	s_cbranch_scc1 .LBB0_1090
	s_bitcmp1_b32 s63, 0
	s_cselect_b32 s61, 0xa800, 0
	s_add_i32 s61, s61, 0
	v_add3_u32 v162, s61, v199, v202
	ds_read_b128 v[66:69], v162
	ds_read_b128 v[146:149], v162 offset:32
	ds_read_b128 v[82:85], v162 offset:12800
	ds_read_b128 v[150:153], v162 offset:64
	ds_read_b128 v[154:157], v162 offset:12832
	ds_read_b128 v[158:161], v162 offset:12864
	s_waitcnt lgkmcnt(3)
	v_mfma_f32_32x32x16_bf16 v[82:97], v[82:85], v[142:145], v[216:231]
	v_mfma_f32_32x32x16_bf16 v[66:81], v[66:69], v[142:145], v[216:231]
	v_mfma_f32_32x32x16_bf16 v[66:81], v[146:149], v[138:141], v[66:81]
	ds_read_b128 v[142:145], v162 offset:96
	ds_read_b128 v[146:149], v162 offset:12896
	s_waitcnt lgkmcnt(3)
	v_mfma_f32_32x32x16_bf16 v[82:97], v[154:157], v[138:141], v[82:97]
	v_mfma_f32_32x32x16_bf16 v[66:81], v[150:153], v[134:137], v[66:81]
	ds_read_b128 v[138:141], v162 offset:128
	ds_read_b128 v[150:153], v162 offset:12928
	s_waitcnt lgkmcnt(4)
	v_mfma_f32_32x32x16_bf16 v[82:97], v[158:161], v[134:137], v[82:97]
	s_waitcnt lgkmcnt(3)
	v_mfma_f32_32x32x16_bf16 v[66:81], v[142:145], v[130:133], v[66:81]
	ds_read_b128 v[134:137], v162 offset:160
	ds_read_b128 v[142:145], v162 offset:12960
	s_waitcnt lgkmcnt(4)
	v_mfma_f32_32x32x16_bf16 v[82:97], v[146:149], v[130:133], v[82:97]
	s_waitcnt lgkmcnt(3)
	v_mfma_f32_32x32x16_bf16 v[66:81], v[138:141], v[126:129], v[66:81]
	ds_read_b128 v[130:133], v162 offset:192
	ds_read_b128 v[138:141], v162 offset:12992
	s_waitcnt lgkmcnt(4)
	v_mfma_f32_32x32x16_bf16 v[82:97], v[150:153], v[126:129], v[82:97]
	s_waitcnt lgkmcnt(3)
	v_mfma_f32_32x32x16_bf16 v[66:81], v[134:137], v[122:125], v[66:81]
	ds_read_b128 v[126:129], v162 offset:224
	ds_read_b128 v[134:137], v162 offset:13024
	s_waitcnt lgkmcnt(4)
	v_mfma_f32_32x32x16_bf16 v[82:97], v[142:145], v[122:125], v[82:97]
	s_waitcnt lgkmcnt(3)
	v_mfma_f32_32x32x16_bf16 v[66:81], v[130:133], v[118:121], v[66:81]
	ds_read_b128 v[122:125], v162 offset:256
	ds_read_b128 v[130:133], v162 offset:13056
	s_waitcnt lgkmcnt(4)
	v_mfma_f32_32x32x16_bf16 v[82:97], v[138:141], v[118:121], v[82:97]
	s_waitcnt lgkmcnt(3)
	v_mfma_f32_32x32x16_bf16 v[66:81], v[126:129], v[114:117], v[66:81]
	ds_read_b128 v[118:121], v162 offset:288
	ds_read_b128 v[126:129], v162 offset:13088
	s_waitcnt lgkmcnt(4)
	v_mfma_f32_32x32x16_bf16 v[82:97], v[134:137], v[114:117], v[82:97]
	s_waitcnt lgkmcnt(3)
	v_mfma_f32_32x32x16_bf16 v[66:81], v[122:125], v[110:113], v[66:81]
	ds_read_b128 v[114:117], v162 offset:320
	ds_read_b128 v[122:125], v162 offset:13120
	s_waitcnt lgkmcnt(4)
	v_mfma_f32_32x32x16_bf16 v[82:97], v[130:133], v[110:113], v[82:97]
	s_waitcnt lgkmcnt(3)
	v_mfma_f32_32x32x16_bf16 v[66:81], v[118:121], v[106:109], v[66:81]
	ds_read_b128 v[110:113], v162 offset:352
	ds_read_b128 v[118:121], v162 offset:13152
	s_waitcnt lgkmcnt(4)
	v_mfma_f32_32x32x16_bf16 v[82:97], v[126:129], v[106:109], v[82:97]
	s_waitcnt lgkmcnt(3)
	v_mfma_f32_32x32x16_bf16 v[66:81], v[114:117], v[102:105], v[66:81]
	s_waitcnt lgkmcnt(2)
	v_mfma_f32_32x32x16_bf16 v[82:97], v[122:125], v[102:105], v[82:97]
	s_waitcnt lgkmcnt(1)
	v_mfma_f32_32x32x16_bf16 v[66:81], v[110:113], v[98:101], v[66:81]
	v_add_u32_e32 v102, s61, v184
	v_add_u32_e32 v122, v102, v189
	v_add_u32_e32 v115, 0x6000, v122
	v_add_u32_e32 v116, 0x7000, v122
	v_add_u32_e32 v117, 0x8000, v122
	ds_read2_b64 v[102:105], v115 offset0:128 offset1:130
	ds_read2_b64 v[110:113], v116 offset0:160 offset1:162
	s_nop 4
	v_max_f32_e32 v106, v66, v67
	s_waitcnt lgkmcnt(2)
	v_mfma_f32_32x32x16_bf16 v[82:97], v[118:121], v[98:101], v[82:97]
	v_max3_f32 v106, v106, v68, v69
	v_max3_f32 v106, v106, v70, v71
	v_max3_f32 v106, v106, v72, v73
	v_max3_f32 v106, v106, v74, v75
	v_max3_f32 v106, v106, v76, v77
	v_max3_f32 v106, v106, v78, v79
	v_max3_f32 v106, v106, v80, v81
	s_nop 4
	v_max3_f32 v98, v106, v82, v83
	v_max3_f32 v98, v98, v84, v85
	v_max3_f32 v98, v98, v86, v87
	v_max3_f32 v98, v98, v88, v89
	v_max3_f32 v98, v98, v90, v91
	v_max3_f32 v98, v98, v92, v93
	v_max3_f32 v98, v98, v94, v95
	v_max3_f32 v98, v98, v96, v97
	ds_bpermute_b32 v99, v185, v98
	v_add_u32_e32 v118, 0x9000, v122
	ds_read2_b64 v[106:109], v117 offset0:192 offset1:194
	s_waitcnt lgkmcnt(1)
	v_max_f32_e32 v237, v98, v99
	v_cmp_lt_f32_e32 vcc, 0x41400000, v237
	ds_read2_b64 v[98:101], v118 offset0:224 offset1:226
	s_cbranch_vccz .Lfold_1_keep

; #define LAS __attribute__((address_space(3)))
; DI float shfl_xor_l(float v, int lane, int m) { return __int_as_float(__builtin_amdgcn_ds_bpermute((lane ^ m) << 2, __float_as_int(v))); }
; #define A_LOAD(kt) do { const size_t ko = (size_t)(kt) * 64; st0 = *(const u32x4*)(kn_src + ko * 2048); st1 = *(const u32x4*)(kn_src + (ko + 32) * 2048); \
;         st2 = *(const u32x4*)(kr_src + ko * 64); st3 = *(const u32x4*)(v_src + ko); st4 = *(const u32x4*)(v_src + ko + (size_t)64 * 8192); } while (0)
; #define VLD(dst, j, dt) do { LAS unsigned char* va_ = vb + (32 * (dt) + n) * VROW + (16 * (j) + 4 * g) * 2; const u32x2 lo_ = *(const LAS u32x2*)(va_), hi_ = *(const LAS u32x2*)(va_ + 16); dst = (u32x4){lo_.x, lo_.y, hi_.x, hi_.y}; } while (0)
; DI void attn_unit(LAS unsigned char* lds, int wid, int b, int h, int qb) {
;     ...
;     for (int kt = 0; kt < nkt; ++kt) {
;         const int buf = kt & 1;
;         if (kt + 1 < nkt) A_LOAD(kt + 1);
;         if (kt <= cq) {
;             LAS unsigned char* kb = lds + buf * ABUF; LAS unsigned char* vb = kb + KBYTES;
;             f32x16 s0, s1;
; #pragma unroll
;             for (int i = 0; i < 16; ++i) { s0[i] = 0.f; s1[i] = 0.f; }
;     ...
;             bf16x8 ka[3][2];
;             ka[0][0] = KLD(0, 0); ka[0][1] = KLD(0, 1); ka[1][0] = KLD(1, 0); ka[1][1] = KLD(1, 1);
; #pragma unroll
;             for (int ks = 0; ks < 12; ++ks) {
;                 if (ks + 2 < 12) { ka[(ks + 2) % 3][0] = KLD(ks + 2, 0); ka[(ks + 2) % 3][1] = KLD(ks + 2, 1); }
;                 s0 = __builtin_amdgcn_mfma_f32_32x32x16_bf16(ka[ks % 3][0], qf[ks], s0, 0, 0, 0); s1 = __builtin_amdgcn_mfma_f32_32x32x16_bf16(ka[ks % 3][1], qf[ks], s1, 0, 0, 0);
;                 __builtin_amdgcn_sched_barrier(0); }
;             u32x4 vf[2][4];
; #pragma unroll
;             for (int dt = 0; dt < 4; ++dt) VLD(vf[0][dt], 0, dt);
;             float mx = s0[0];
; #pragma unroll
;             for (int i = 1; i < 16; ++i) mx = fmaxf(mx, s0[i]);
; #pragma unroll
;             for (int i = 0; i < 16; ++i) mx = fmaxf(mx, s1[i]);
;             mx = fmaxf(mx, shfl_xor_l(mx, lane, 32));
;             const float mnew = fmaxf(mrow, mx), alpha = __builtin_amdgcn_exp2f(mrow - mnew); mrow = mnew;
.LBB0_1091:
	s_and_b32 s18, s57, 1
	global_load_dwordx4 v[2:5], v198, s[70:71]
	global_load_dwordx4 v[6:9], v198, s[72:73]
	global_load_dwordx4 v[10:13], v196, s[78:79]
	global_load_dwordx4 v[160:163], v194, s[74:75] offset:128
	global_load_dwordx4 v[164:167], v194, s[76:77] offset:128
	s_cmp_gt_u32 s57, s25
	s_cbranch_scc1 .LBB0_1095
	s_mul_i32 s19, s18, 0xa800
	s_add_i32 s19, s19, 0
	v_add3_u32 v0, s19, v193, v204
	ds_read_b128 v[80:83], v0
	ds_read_b128 v[168:171], v0 offset:32
	ds_read_b128 v[96:99], v0 offset:12800
	ds_read_b128 v[174:177], v0 offset:64
	ds_read_b128 v[178:181], v0 offset:12832
	ds_read_b128 v[206:209], v0 offset:12864
	s_waitcnt vmcnt(6) lgkmcnt(3)
	v_mfma_f32_32x32x16_bf16 v[96:111], v[96:99], v[156:159], v[216:231]
	v_mfma_f32_32x32x16_bf16 v[80:95], v[80:83], v[156:159], v[216:231]
	v_mfma_f32_32x32x16_bf16 v[80:95], v[168:171], v[152:155], v[80:95]
	ds_read_b128 v[168:171], v0 offset:96
	ds_read_b128 v[210:213], v0 offset:12896
	s_waitcnt lgkmcnt(3)
	v_mfma_f32_32x32x16_bf16 v[96:111], v[178:181], v[152:155], v[96:111]
	v_mfma_f32_32x32x16_bf16 v[80:95], v[174:177], v[148:151], v[80:95]
	ds_read_b128 v[174:177], v0 offset:128
	ds_read_b128 v[178:181], v0 offset:12928
	s_waitcnt lgkmcnt(4)
	v_mfma_f32_32x32x16_bf16 v[96:111], v[206:209], v[148:151], v[96:111]
	s_waitcnt lgkmcnt(3)
	v_mfma_f32_32x32x16_bf16 v[80:95], v[168:171], v[144:147], v[80:95]
	ds_read_b128 v[168:171], v0 offset:160
	ds_read_b128 v[206:209], v0 offset:12960
	s_waitcnt lgkmcnt(4)
	v_mfma_f32_32x32x16_bf16 v[96:111], v[210:213], v[144:147], v[96:111]
	s_waitcnt lgkmcnt(3)
	v_mfma_f32_32x32x16_bf16 v[80:95], v[174:177], v[140:143], v[80:95]
	ds_read_b128 v[174:177], v0 offset:192
	ds_read_b128 v[210:213], v0 offset:12992
	s_waitcnt lgkmcnt(4)
	v_mfma_f32_32x32x16_bf16 v[96:111], v[178:181], v[140:143], v[96:111]
	s_waitcnt lgkmcnt(3)
	v_mfma_f32_32x32x16_bf16 v[80:95], v[168:171], v[136:139], v[80:95]
	ds_read_b128 v[168:171], v0 offset:224
	ds_read_b128 v[178:181], v0 offset:13024
	s_waitcnt lgkmcnt(4)
	v_mfma_f32_32x32x16_bf16 v[96:111], v[206:209], v[136:139], v[96:111]
	s_waitcnt lgkmcnt(3)
	v_mfma_f32_32x32x16_bf16 v[80:95], v[174:177], v[132:135], v[80:95]
	ds_read_b128 v[174:177], v0 offset:256
	ds_read_b128 v[206:209], v0 offset:13056
	s_waitcnt lgkmcnt(4)
	v_mfma_f32_32x32x16_bf16 v[96:111], v[210:213], v[132:135], v[96:111]
	s_waitcnt lgkmcnt(3)
	v_mfma_f32_32x32x16_bf16 v[80:95], v[168:171], v[128:131], v[80:95]
	ds_read_b128 v[168:171], v0 offset:288
	ds_read_b128 v[210:213], v0 offset:13088
	s_waitcnt lgkmcnt(4)
	v_mfma_f32_32x32x16_bf16 v[96:111], v[178:181], v[128:131], v[96:111]
	s_waitcnt lgkmcnt(3)
	v_mfma_f32_32x32x16_bf16 v[80:95], v[174:177], v[124:127], v[80:95]
	ds_read_b128 v[174:177], v0 offset:320
	ds_read_b128 v[178:181], v0 offset:13120
	s_waitcnt lgkmcnt(4)
	v_mfma_f32_32x32x16_bf16 v[96:111], v[206:209], v[124:127], v[96:111]
	s_waitcnt lgkmcnt(3)
	v_mfma_f32_32x32x16_bf16 v[80:95], v[168:171], v[120:123], v[80:95]
	ds_read_b128 v[168:171], v0 offset:352
	ds_read_b128 v[206:209], v0 offset:13152
	s_waitcnt lgkmcnt(4)
	v_mfma_f32_32x32x16_bf16 v[96:111], v[210:213], v[120:123], v[96:111]
	s_waitcnt lgkmcnt(3)
	v_mfma_f32_32x32x16_bf16 v[80:95], v[174:177], v[116:119], v[80:95]
	s_waitcnt lgkmcnt(2)
	v_mfma_f32_32x32x16_bf16 v[96:111], v[178:181], v[116:119], v[96:111]
	s_waitcnt vmcnt(5) lgkmcnt(1)
	v_mfma_f32_32x32x16_bf16 v[80:95], v[168:171], v[112:115], v[80:95]
	v_add3_u32 v173, s19, v188, v191
	v_add_u32_e32 v15, 0x6000, v173
	v_add_u32_e32 v205, 0x7000, v173
	ds_read2_b64 v[168:171], v15 offset0:128 offset1:130
	ds_read2_b64 v[180:183], v205 offset0:160 offset1:162
	s_nop 5
	v_max_f32_e32 v0, v80, v81
	s_waitcnt lgkmcnt(2)
	v_mfma_f32_32x32x16_bf16 v[96:111], v[206:209], v[112:115], v[96:111]
	v_max3_f32 v0, v0, v82, v83
	v_max3_f32 v0, v0, v84, v85
	v_max3_f32 v0, v0, v86, v87
	v_max3_f32 v0, v0, v88, v89
	v_max3_f32 v0, v0, v90, v91
	v_max3_f32 v0, v0, v92, v93
	v_max3_f32 v0, v0, v94, v95
	s_nop 4
	v_max3_f32 v0, v0, v96, v97
	v_max3_f32 v0, v0, v98, v99
	v_max3_f32 v0, v0, v100, v101
	v_max3_f32 v0, v0, v102, v103
	v_max3_f32 v0, v0, v104, v105
	v_max3_f32 v0, v0, v106, v107
	v_max3_f32 v0, v0, v108, v109
	v_max3_f32 v0, v0, v110, v111
	v_add_u32_e32 v206, 0x8000, v173
	v_add_u32_e32 v207, 0x9000, v173
	ds_read2_b64 v[176:179], v206 offset0:192 offset1:194
	v_cmp_lt_f32_e32 vcc, 0x41400000, v0
	ds_read2_b64 v[172:175], v207 offset0:224 offset1:226
	s_cmp_eq_u32 s57, 0
	s_cbranch_scc1 .Lfold_2_upd
	s_cbranch_vccnz .Lfold_2_upd

; #define LAS __attribute__((address_space(3)))
; DI float shfl_xor_l(float v, int lane, int m) { return __int_as_float(__builtin_amdgcn_ds_bpermute((lane ^ m) << 2, __float_as_int(v))); }
; #define VLD(dst, j, dt) do { LAS unsigned char* va_ = vb + (32 * (dt) + n) * VROW + (16 * (j) + 4 * g) * 2; const u32x2 lo_ = *(const LAS u32x2*)(va_), hi_ = *(const LAS u32x2*)(va_ + 16); dst = (u32x4){lo_.x, lo_.y, hi_.x, hi_.y}; } while (0)
; DI void attn_unit(LAS unsigned char* lds, int wid, int b, int h, int qb) {
;     ...
;         if (kt <= cq) {
;             LAS unsigned char* kb = lds + buf * ABUF; LAS unsigned char* vb = kb + KBYTES;
;             f32x16 s0, s1;
; #pragma unroll
;             for (int i = 0; i < 16; ++i) { s0[i] = 0.f; s1[i] = 0.f; }
;     ...
;             bf16x8 ka[3][2];
;             ka[0][0] = KLD(0, 0); ka[0][1] = KLD(0, 1); ka[1][0] = KLD(1, 0); ka[1][1] = KLD(1, 1);
; #pragma unroll
;             for (int ks = 0; ks < 12; ++ks) {
;                 if (ks + 2 < 12) { ka[(ks + 2) % 3][0] = KLD(ks + 2, 0); ka[(ks + 2) % 3][1] = KLD(ks + 2, 1); }
;                 s0 = __builtin_amdgcn_mfma_f32_32x32x16_bf16(ka[ks % 3][0], qf[ks], s0, 0, 0, 0); s1 = __builtin_amdgcn_mfma_f32_32x32x16_bf16(ka[ks % 3][1], qf[ks], s1, 0, 0, 0);
;                 __builtin_amdgcn_sched_barrier(0); }
;             u32x4 vf[2][4];
; #pragma unroll
;             for (int dt = 0; dt < 4; ++dt) VLD(vf[0][dt], 0, dt);
;             float mx = s0[0];
; #pragma unroll
;             for (int i = 1; i < 16; ++i) mx = fmaxf(mx, s0[i]);
; #pragma unroll
;             for (int i = 0; i < 16; ++i) mx = fmaxf(mx, s1[i]);
;             mx = fmaxf(mx, shfl_xor_l(mx, lane, 32));
;             const float mnew = fmaxf(mrow, mx), alpha = __builtin_amdgcn_exp2f(mrow - mnew); mrow = mnew;
;             float ls = 0.f;
; #pragma unroll
;             for (int i = 0; i < 16; ++i) { s0[i] = __builtin_amdgcn_exp2f(s0[i] - mnew); s1[i] = __builtin_amdgcn_exp2f(s1[i] - mnew); ls += s0[i] + s1[i]; }
;             lrow = lrow * alpha + ls;
;             if (__builtin_amdgcn_ballot_w64(alpha != 1.f) != 0ull) {
.LBB0_1098:
	s_lshl_b32 s18, s56, 2
	s_or_b32 s18, s18, 2
	s_cmp_ge_u32 s18, s25
	s_cbranch_scc1 .LBB0_1077
	s_bitcmp1_b32 s4, 0
	s_cselect_b32 s4, 0xa800, 0
	s_add_i32 s4, s4, 0
	v_add3_u32 v0, s4, v193, v204
	ds_read_b128 v[2:5], v0
	ds_read_b128 v[6:9], v0 offset:32
	s_waitcnt lgkmcnt(1)
	v_mfma_f32_32x32x16_bf16 v[80:95], v[2:5], v[156:159], v[216:231]
	ds_read_b128 v[2:5], v0 offset:12800
	ds_read_b128 v[10:13], v0 offset:64
	ds_read_b128 v[160:163], v0 offset:12832
	ds_read_b128 v[164:167], v0 offset:12864
	s_waitcnt lgkmcnt(3)
	v_mfma_f32_32x32x16_bf16 v[96:111], v[2:5], v[156:159], v[216:231]
	v_mfma_f32_32x32x16_bf16 v[80:95], v[6:9], v[152:155], v[80:95]
	ds_read_b128 v[2:5], v0 offset:96
	ds_read_b128 v[6:9], v0 offset:12896
	s_waitcnt lgkmcnt(3)
	v_mfma_f32_32x32x16_bf16 v[96:111], v[160:163], v[152:155], v[96:111]
	v_mfma_f32_32x32x16_bf16 v[80:95], v[10:13], v[148:151], v[80:95]
	ds_read_b128 v[10:13], v0 offset:128
	ds_read_b128 v[152:155], v0 offset:12928
	s_waitcnt lgkmcnt(4)
	v_mfma_f32_32x32x16_bf16 v[96:111], v[164:167], v[148:151], v[96:111]
	s_waitcnt lgkmcnt(3)
	v_mfma_f32_32x32x16_bf16 v[80:95], v[2:5], v[144:147], v[80:95]
	ds_read_b128 v[2:5], v0 offset:160
	ds_read_b128 v[148:151], v0 offset:12960
	s_waitcnt lgkmcnt(4)
	v_mfma_f32_32x32x16_bf16 v[96:111], v[6:9], v[144:147], v[96:111]
	s_waitcnt lgkmcnt(3)
	v_mfma_f32_32x32x16_bf16 v[80:95], v[10:13], v[140:143], v[80:95]
	ds_read_b128 v[6:9], v0 offset:192
	ds_read_b128 v[10:13], v0 offset:12992
	s_waitcnt lgkmcnt(4)
	v_mfma_f32_32x32x16_bf16 v[96:111], v[152:155], v[140:143], v[96:111]
	s_waitcnt lgkmcnt(3)
	v_mfma_f32_32x32x16_bf16 v[80:95], v[2:5], v[136:139], v[80:95]
	ds_read_b128 v[2:5], v0 offset:224
	ds_read_b128 v[140:143], v0 offset:13024
	s_waitcnt lgkmcnt(4)
	v_mfma_f32_32x32x16_bf16 v[96:111], v[148:151], v[136:139], v[96:111]
	s_waitcnt lgkmcnt(3)
	v_mfma_f32_32x32x16_bf16 v[80:95], v[6:9], v[132:135], v[80:95]
	ds_read_b128 v[6:9], v0 offset:256
	ds_read_b128 v[136:139], v0 offset:13056
	s_waitcnt lgkmcnt(4)
	v_mfma_f32_32x32x16_bf16 v[96:111], v[10:13], v[132:135], v[96:111]
	s_waitcnt lgkmcnt(3)
	v_mfma_f32_32x32x16_bf16 v[80:95], v[2:5], v[128:131], v[80:95]
	ds_read_b128 v[2:5], v0 offset:288
	ds_read_b128 v[10:13], v0 offset:13088
	s_waitcnt lgkmcnt(4)
	v_mfma_f32_32x32x16_bf16 v[96:111], v[140:143], v[128:131], v[96:111]
	s_waitcnt lgkmcnt(3)
	v_mfma_f32_32x32x16_bf16 v[80:95], v[6:9], v[124:127], v[80:95]
	ds_read_b128 v[6:9], v0 offset:320
	ds_read_b128 v[128:131], v0 offset:13120
	s_waitcnt lgkmcnt(4)
	v_mfma_f32_32x32x16_bf16 v[96:111], v[136:139], v[124:127], v[96:111]
	s_waitcnt lgkmcnt(3)
	v_mfma_f32_32x32x16_bf16 v[80:95], v[2:5], v[120:123], v[80:95]
	ds_read_b128 v[2:5], v0 offset:352
	ds_read_b128 v[124:127], v0 offset:13152
	s_waitcnt lgkmcnt(4)
	v_mfma_f32_32x32x16_bf16 v[96:111], v[10:13], v[120:123], v[96:111]
	s_waitcnt lgkmcnt(3)
	v_mfma_f32_32x32x16_bf16 v[80:95], v[6:9], v[116:119], v[80:95]
	s_waitcnt lgkmcnt(2)
	v_mfma_f32_32x32x16_bf16 v[96:111], v[128:131], v[116:119], v[96:111]
	s_waitcnt lgkmcnt(1)
	v_mfma_f32_32x32x16_bf16 v[80:95], v[2:5], v[112:115], v[80:95]
	v_add_u32_e32 v0, s4, v188
	v_add_u32_e32 v6, v0, v191
	v_add_u32_e32 v15, 0x6000, v6
	v_add_u32_e32 v116, 0x7000, v6
	v_add_u32_e32 v117, 0x8000, v6
	ds_read2_b64 v[2:5], v15 offset0:128 offset1:130
	ds_read2_b64 v[10:13], v117 offset0:192 offset1:194
	s_nop 4
	v_max_f32_e32 v0, v80, v81
	s_waitcnt lgkmcnt(2)
	v_mfma_f32_32x32x16_bf16 v[96:111], v[124:127], v[112:115], v[96:111]
	v_max3_f32 v0, v0, v82, v83
	v_max3_f32 v0, v0, v84, v85
	v_max3_f32 v0, v0, v86, v87
	v_max3_f32 v0, v0, v88, v89
	v_max3_f32 v0, v0, v90, v91
	v_max3_f32 v0, v0, v92, v93
	v_max3_f32 v0, v0, v94, v95
	s_nop 4
	v_max3_f32 v0, v0, v96, v97
	v_max3_f32 v0, v0, v98, v99
	v_max3_f32 v0, v0, v100, v101
	v_max3_f32 v0, v0, v102, v103
	v_max3_f32 v0, v0, v104, v105
	v_max3_f32 v0, v0, v106, v107
	v_max3_f32 v0, v0, v108, v109
	v_max3_f32 v0, v0, v110, v111
	ds_bpermute_b32 v7, v189, v0
	ds_read2_b64 v[112:115], v116 offset0:160 offset1:162
	s_waitcnt lgkmcnt(1)
	v_max_f32_e32 v237, v0, v7
	v_add_u32_e32 v14, 0x9000, v6
	v_cmp_lt_f32_e32 vcc, 0x41400000, v237
	ds_read2_b64 v[6:9], v14 offset0:224 offset1:226
	s_cbranch_vccz .Lfold_3_keep
